# GATES: next-ticket atomic issued at loop head and consumed after the K loop; epilogue no longer waits for prefetch DMAs
# speedup vs baseline: 1.0008x; 1.0008x over previous
.Lgt_ein:
	s_waitcnt vmcnt(12)
	v_cvt_f32_i32_e32 v132, v89
	v_lshrrev_b32_e32 v89, 2, v92
	ds_read_b128 v[104:107], v96
	ds_read_b128 v[108:111], v96 offset:32
	ds_read_b128 v[112:115], v96 offset:64
	ds_read_b128 v[128:131], v96 offset:96
	ds_read_b128 v[76:79], v96 offset:128
	ds_read_b128 v[72:75], v96 offset:160
	ds_read_b128 v[68:71], v96 offset:192
	ds_read_b128 v[64:67], v96 offset:224
	v_cvt_f32_i32_e32 v134, v91
	v_add_u32_e32 v89, v89, v93
	v_and_b32_e32 v91, 7, v93
	s_movk_i32 s13, 0xff8
	v_mov_b32_e32 v133, v55
	s_waitcnt lgkmcnt(0)
	v_mov_b32_e32 v119, v111
	s_and_b64 s[16:17], exec, s[40:41]
	v_and_or_b32 v89, v89, s13, v91
	v_pk_mul_f32 v[132:133], v[132:133], v[118:119]
	s_or_b64 s[14:15], s[16:17], s[14:15]
	v_lshlrev_b32_e32 v116, 15, v89
	v_fma_f32 v48, v48, v104, v132
	v_fma_f32 v49, v49, v105, v132
	v_fma_f32 v50, v50, v106, v132
	v_fma_f32 v51, v51, v107, v132
	v_fma_f32 v52, v52, v108, v132
	v_fma_f32 v53, v53, v109, v132
	v_fma_f32 v54, v54, v110, v132
	v_add_f32_e32 v55, v132, v133
	v_fma_f32 v56, v56, v112, v132
	v_fma_f32 v57, v57, v113, v132
	v_fma_f32 v58, v58, v114, v132
	v_fma_f32 v59, v59, v115, v132
	v_fma_f32 v60, v60, v128, v132
	v_fma_f32 v61, v61, v129, v132
	v_fma_f32 v62, v62, v130, v132
	v_fma_f32 v63, v63, v131, v132
	v_lshl_add_u64 v[92:93], v[86:87], 0, v[116:117]
	v_mul_f32_e32 v48, 0xbfb8aa3b, v48
	v_mul_f32_e32 v49, 0xbfb8aa3b, v49
	v_mul_f32_e32 v50, 0xbfb8aa3b, v50
	v_mul_f32_e32 v51, 0xbfb8aa3b, v51
	v_mul_f32_e32 v52, 0xbfb8aa3b, v52
	v_mul_f32_e32 v53, 0xbfb8aa3b, v53
	v_mul_f32_e32 v54, 0xbfb8aa3b, v54
	v_mul_f32_e32 v55, 0xbfb8aa3b, v55
	v_mul_f32_e32 v56, 0xbfb8aa3b, v56
	v_mul_f32_e32 v57, 0xbfb8aa3b, v57
	v_mul_f32_e32 v58, 0xbfb8aa3b, v58
	v_mul_f32_e32 v59, 0xbfb8aa3b, v59
	v_mul_f32_e32 v60, 0xbfb8aa3b, v60
	v_mul_f32_e32 v61, 0xbfb8aa3b, v61
	v_mul_f32_e32 v62, 0xbfb8aa3b, v62
	v_mul_f32_e32 v63, 0xbfb8aa3b, v63
	v_exp_f32_e32 v48, v48
	v_exp_f32_e32 v49, v49
	v_exp_f32_e32 v50, v50
	v_exp_f32_e32 v51, v51
	v_exp_f32_e32 v52, v52
	v_exp_f32_e32 v53, v53
	v_exp_f32_e32 v54, v54
	v_exp_f32_e32 v55, v55
	v_exp_f32_e32 v56, v56
	v_exp_f32_e32 v57, v57
	v_exp_f32_e32 v58, v58
	v_exp_f32_e32 v59, v59
	v_exp_f32_e32 v60, v60
	v_exp_f32_e32 v61, v61
	v_exp_f32_e32 v62, v62
	v_exp_f32_e32 v63, v63
	v_add_f32_e32 v48, 1.0, v48
	v_add_f32_e32 v49, 1.0, v49
	v_add_f32_e32 v50, 1.0, v50
	v_add_f32_e32 v51, 1.0, v51
	v_add_f32_e32 v52, 1.0, v52
	v_add_f32_e32 v53, 1.0, v53
	v_add_f32_e32 v54, 1.0, v54
	v_add_f32_e32 v55, 1.0, v55
	v_add_f32_e32 v56, 1.0, v56
	v_add_f32_e32 v57, 1.0, v57
	v_add_f32_e32 v58, 1.0, v58
	v_add_f32_e32 v59, 1.0, v59
	v_add_f32_e32 v60, 1.0, v60
	v_add_f32_e32 v61, 1.0, v61
	v_add_f32_e32 v62, 1.0, v62
	v_add_f32_e32 v63, 1.0, v63
	v_rcp_f32_e32 v48, v48
	v_rcp_f32_e32 v49, v49
	v_rcp_f32_e32 v50, v50
	v_rcp_f32_e32 v51, v51
	v_rcp_f32_e32 v52, v52
	v_rcp_f32_e32 v53, v53
	v_rcp_f32_e32 v54, v54
	v_rcp_f32_e32 v55, v55
	v_rcp_f32_e32 v56, v56
	v_rcp_f32_e32 v57, v57
	v_rcp_f32_e32 v58, v58
	v_rcp_f32_e32 v59, v59
	v_rcp_f32_e32 v60, v60
	v_rcp_f32_e32 v61, v61
	v_rcp_f32_e32 v62, v62
	v_rcp_f32_e32 v63, v63
	s_movk_i32 s13, 0x2000
	v_cvt_pk_bf16_f32 v48, v48, v49
	v_cvt_pk_bf16_f32 v49, v50, v51
	v_cvt_pk_bf16_f32 v50, v52, v53
	v_cvt_pk_bf16_f32 v51, v54, v55
	v_add_co_u32_e32 v52, vcc, s13, v92
	global_store_dwordx4 v[92:93], v[48:51], off
	s_nop 0
	v_addc_co_u32_e32 v53, vcc, 0, v93, vcc
	v_cvt_pk_bf16_f32 v48, v56, v57
	v_cvt_pk_bf16_f32 v49, v58, v59
	v_cvt_pk_bf16_f32 v50, v60, v61
	v_cvt_pk_bf16_f32 v51, v62, v63
	v_mov_b32_e32 v135, v39
	global_store_dwordx4 v[52:53], v[48:51], off offset:-4096
	s_nop 1
	v_pk_mul_f32 v[48:49], v[134:135], v[118:119]
	s_nop 0
	v_fma_f32 v32, v32, v104, v48
	v_fma_f32 v33, v33, v105, v48
	v_fma_f32 v34, v34, v106, v48
	v_fma_f32 v35, v35, v107, v48
	v_fma_f32 v36, v36, v108, v48
	v_fma_f32 v37, v37, v109, v48
	v_fma_f32 v38, v38, v110, v48
	v_add_f32_e32 v39, v48, v49
	v_fma_f32 v40, v40, v112, v48
	v_fma_f32 v41, v41, v113, v48
	v_fma_f32 v42, v42, v114, v48
	v_fma_f32 v43, v43, v115, v48
	v_fma_f32 v44, v44, v128, v48
	v_fma_f32 v45, v45, v129, v48
	v_fma_f32 v46, v46, v130, v48
	v_fma_f32 v47, v47, v131, v48
	v_mul_f32_e32 v32, 0xbfb8aa3b, v32
	v_mul_f32_e32 v33, 0xbfb8aa3b, v33
	v_mul_f32_e32 v34, 0xbfb8aa3b, v34
	v_mul_f32_e32 v35, 0xbfb8aa3b, v35
	v_mul_f32_e32 v36, 0xbfb8aa3b, v36
	v_mul_f32_e32 v37, 0xbfb8aa3b, v37
	v_mul_f32_e32 v38, 0xbfb8aa3b, v38
	v_mul_f32_e32 v39, 0xbfb8aa3b, v39
	v_mul_f32_e32 v40, 0xbfb8aa3b, v40
	v_mul_f32_e32 v41, 0xbfb8aa3b, v41
	v_mul_f32_e32 v42, 0xbfb8aa3b, v42
	v_mul_f32_e32 v43, 0xbfb8aa3b, v43
	v_mul_f32_e32 v44, 0xbfb8aa3b, v44
	v_mul_f32_e32 v45, 0xbfb8aa3b, v45
	v_mul_f32_e32 v46, 0xbfb8aa3b, v46
	v_mul_f32_e32 v47, 0xbfb8aa3b, v47
	v_exp_f32_e32 v32, v32
	v_exp_f32_e32 v33, v33
	v_exp_f32_e32 v34, v34
	v_exp_f32_e32 v35, v35
	v_exp_f32_e32 v36, v36
	v_exp_f32_e32 v37, v37
	v_exp_f32_e32 v38, v38
	v_exp_f32_e32 v39, v39
	v_exp_f32_e32 v40, v40
	v_exp_f32_e32 v41, v41
	v_exp_f32_e32 v42, v42
	v_exp_f32_e32 v43, v43
	v_exp_f32_e32 v44, v44
	v_exp_f32_e32 v45, v45
	v_exp_f32_e32 v46, v46
	v_exp_f32_e32 v47, v47
	v_add_f32_e32 v32, 1.0, v32
	v_add_f32_e32 v33, 1.0, v33
	v_add_f32_e32 v34, 1.0, v34
	v_add_f32_e32 v35, 1.0, v35
	v_add_f32_e32 v36, 1.0, v36
	v_add_f32_e32 v37, 1.0, v37
	v_add_f32_e32 v38, 1.0, v38
	v_add_f32_e32 v39, 1.0, v39
	v_add_f32_e32 v40, 1.0, v40
	v_add_f32_e32 v41, 1.0, v41
	v_add_f32_e32 v42, 1.0, v42
	v_add_f32_e32 v43, 1.0, v43
	v_add_f32_e32 v44, 1.0, v44
	v_add_f32_e32 v45, 1.0, v45
	v_add_f32_e32 v46, 1.0, v46
	v_add_f32_e32 v47, 1.0, v47
	v_rcp_f32_e32 v32, v32
	v_rcp_f32_e32 v33, v33
	v_rcp_f32_e32 v34, v34
	v_rcp_f32_e32 v35, v35
	v_rcp_f32_e32 v36, v36
	v_rcp_f32_e32 v37, v37
	v_rcp_f32_e32 v38, v38
	v_rcp_f32_e32 v39, v39
	v_rcp_f32_e32 v40, v40
	v_rcp_f32_e32 v41, v41
	v_rcp_f32_e32 v42, v42
	v_rcp_f32_e32 v43, v43
	v_rcp_f32_e32 v44, v44
	v_rcp_f32_e32 v45, v45
	v_rcp_f32_e32 v46, v46
	v_rcp_f32_e32 v47, v47
	s_movk_i32 s13, 0x4000
	v_cvt_pk_bf16_f32 v32, v32, v33
	v_cvt_pk_bf16_f32 v33, v34, v35
	v_cvt_pk_bf16_f32 v34, v36, v37
	v_cvt_pk_bf16_f32 v35, v38, v39
	v_add_co_u32_e32 v36, vcc, s13, v92
	global_store_dwordx4 v[52:53], v[32:35], off
	s_nop 0
	v_addc_co_u32_e32 v37, vcc, 0, v93, vcc
	v_cvt_pk_bf16_f32 v32, v40, v41
	v_cvt_pk_bf16_f32 v33, v42, v43
	v_cvt_pk_bf16_f32 v34, v44, v45
	v_cvt_pk_bf16_f32 v35, v46, v47
	v_fma_f32 v16, v16, v76, v132
	v_fma_f32 v17, v17, v77, v132
	v_fma_f32 v18, v18, v78, v132
	v_fma_f32 v19, v19, v79, v132
	v_fma_f32 v20, v20, v72, v132
	v_fma_f32 v21, v21, v73, v132
	v_fma_f32 v22, v22, v74, v132
	v_fma_f32 v23, v23, v75, v132
	v_fma_f32 v24, v24, v68, v132
	v_fma_f32 v25, v25, v69, v132
	v_fma_f32 v26, v26, v70, v132
	v_fma_f32 v27, v27, v71, v132
	v_fma_f32 v28, v28, v64, v132
	v_fma_f32 v29, v29, v65, v132
	v_fma_f32 v30, v30, v66, v132
	v_fmac_f32_e32 v132, v31, v67
	global_store_dwordx4 v[36:37], v[32:35], off offset:-4096
	v_mul_f32_e32 v16, 0xbfb8aa3b, v16
	v_mul_f32_e32 v17, 0xbfb8aa3b, v17
	v_mul_f32_e32 v18, 0xbfb8aa3b, v18
	v_mul_f32_e32 v19, 0xbfb8aa3b, v19
	v_mul_f32_e32 v20, 0xbfb8aa3b, v20
	v_mul_f32_e32 v21, 0xbfb8aa3b, v21
	v_mul_f32_e32 v22, 0xbfb8aa3b, v22
	v_mul_f32_e32 v23, 0xbfb8aa3b, v23
	v_mul_f32_e32 v24, 0xbfb8aa3b, v24
	v_mul_f32_e32 v25, 0xbfb8aa3b, v25
	v_mul_f32_e32 v26, 0xbfb8aa3b, v26
	v_mul_f32_e32 v27, 0xbfb8aa3b, v27
	v_mul_f32_e32 v28, 0xbfb8aa3b, v28
	v_mul_f32_e32 v29, 0xbfb8aa3b, v29
	v_mul_f32_e32 v30, 0xbfb8aa3b, v30
	v_mul_f32_e32 v31, 0xbfb8aa3b, v132
	v_exp_f32_e32 v16, v16
	v_exp_f32_e32 v17, v17
	v_exp_f32_e32 v18, v18
	v_exp_f32_e32 v19, v19
	v_exp_f32_e32 v20, v20
	v_exp_f32_e32 v21, v21
	v_exp_f32_e32 v22, v22
	v_exp_f32_e32 v23, v23
	v_exp_f32_e32 v24, v24
	v_exp_f32_e32 v25, v25
	v_exp_f32_e32 v26, v26
	v_exp_f32_e32 v27, v27
	v_exp_f32_e32 v28, v28
	v_exp_f32_e32 v29, v29
	v_exp_f32_e32 v30, v30
	v_exp_f32_e32 v31, v31
	v_add_f32_e32 v16, 1.0, v16
	v_add_f32_e32 v17, 1.0, v17
	v_add_f32_e32 v18, 1.0, v18
	v_add_f32_e32 v19, 1.0, v19
	v_add_f32_e32 v20, 1.0, v20
	v_add_f32_e32 v21, 1.0, v21
	v_add_f32_e32 v22, 1.0, v22
	v_add_f32_e32 v23, 1.0, v23
	v_add_f32_e32 v24, 1.0, v24
	v_add_f32_e32 v25, 1.0, v25
	v_add_f32_e32 v26, 1.0, v26
	v_add_f32_e32 v27, 1.0, v27
	v_add_f32_e32 v28, 1.0, v28
	v_add_f32_e32 v29, 1.0, v29
	v_add_f32_e32 v30, 1.0, v30
	v_add_f32_e32 v31, 1.0, v31
	v_rcp_f32_e32 v16, v16
	v_rcp_f32_e32 v17, v17
	v_rcp_f32_e32 v18, v18
	v_rcp_f32_e32 v19, v19
	v_rcp_f32_e32 v20, v20
	v_rcp_f32_e32 v21, v21
	v_rcp_f32_e32 v22, v22
	v_rcp_f32_e32 v23, v23
	v_rcp_f32_e32 v24, v24
	v_rcp_f32_e32 v25, v25
	v_rcp_f32_e32 v26, v26
	v_rcp_f32_e32 v27, v27
	v_rcp_f32_e32 v28, v28
	v_rcp_f32_e32 v29, v29
	v_rcp_f32_e32 v30, v30
	v_rcp_f32_e32 v31, v31
	v_cvt_pk_bf16_f32 v16, v16, v17
	v_cvt_pk_bf16_f32 v17, v18, v19
	v_cvt_pk_bf16_f32 v18, v20, v21
	v_cvt_pk_bf16_f32 v19, v22, v23
	v_add_co_u32_e32 v20, vcc, s33, v92
	v_fma_f32 v0, v0, v76, v48
	global_store_dwordx4 v[36:37], v[16:19], off
	v_addc_co_u32_e32 v21, vcc, 0, v93, vcc
	s_nop 0
	v_cvt_pk_bf16_f32 v16, v24, v25
	v_cvt_pk_bf16_f32 v17, v26, v27
	v_cvt_pk_bf16_f32 v18, v28, v29
	v_cvt_pk_bf16_f32 v19, v30, v31
	v_fma_f32 v1, v1, v77, v48
	v_fma_f32 v2, v2, v78, v48
	v_fma_f32 v3, v3, v79, v48
	v_fma_f32 v4, v4, v72, v48
	v_fma_f32 v5, v5, v73, v48
	v_fma_f32 v6, v6, v74, v48
	v_fma_f32 v7, v7, v75, v48
	v_fma_f32 v8, v8, v68, v48
	v_fma_f32 v9, v9, v69, v48
	v_fma_f32 v10, v10, v70, v48
	v_fma_f32 v11, v11, v71, v48
	v_fma_f32 v12, v12, v64, v48
	v_fma_f32 v13, v13, v65, v48
	v_fma_f32 v14, v14, v66, v48
	v_fmac_f32_e32 v48, v15, v67
	v_mul_f32_e32 v0, 0xbfb8aa3b, v0
	global_store_dwordx4 v[20:21], v[16:19], off offset:-4096
	v_mul_f32_e32 v1, 0xbfb8aa3b, v1
	v_mul_f32_e32 v2, 0xbfb8aa3b, v2
	v_mul_f32_e32 v3, 0xbfb8aa3b, v3
	v_mul_f32_e32 v4, 0xbfb8aa3b, v4
	v_mul_f32_e32 v5, 0xbfb8aa3b, v5
	v_mul_f32_e32 v6, 0xbfb8aa3b, v6
	v_mul_f32_e32 v7, 0xbfb8aa3b, v7
	v_mul_f32_e32 v8, 0xbfb8aa3b, v8
	v_mul_f32_e32 v9, 0xbfb8aa3b, v9
	v_mul_f32_e32 v10, 0xbfb8aa3b, v10
	v_mul_f32_e32 v11, 0xbfb8aa3b, v11
	v_mul_f32_e32 v12, 0xbfb8aa3b, v12
	v_mul_f32_e32 v13, 0xbfb8aa3b, v13
	v_mul_f32_e32 v14, 0xbfb8aa3b, v14
	v_mul_f32_e32 v15, 0xbfb8aa3b, v48
	v_exp_f32_e32 v0, v0
	v_exp_f32_e32 v1, v1
	v_exp_f32_e32 v2, v2
	v_exp_f32_e32 v3, v3
	v_exp_f32_e32 v4, v4
	v_exp_f32_e32 v5, v5
	v_exp_f32_e32 v6, v6
	v_exp_f32_e32 v7, v7
	v_exp_f32_e32 v8, v8
	v_exp_f32_e32 v9, v9
	v_exp_f32_e32 v10, v10
	v_exp_f32_e32 v11, v11
	v_exp_f32_e32 v12, v12
	v_exp_f32_e32 v13, v13
	v_exp_f32_e32 v14, v14
	v_exp_f32_e32 v15, v15
	v_add_f32_e32 v0, 1.0, v0
	v_rcp_f32_e32 v0, v0
	v_add_f32_e32 v1, 1.0, v1
	v_add_f32_e32 v2, 1.0, v2
	v_add_f32_e32 v3, 1.0, v3
	v_add_f32_e32 v4, 1.0, v4
	v_add_f32_e32 v5, 1.0, v5
	v_add_f32_e32 v6, 1.0, v6
	v_add_f32_e32 v7, 1.0, v7
	v_add_f32_e32 v8, 1.0, v8
	v_add_f32_e32 v9, 1.0, v9
	v_add_f32_e32 v10, 1.0, v10
	v_add_f32_e32 v11, 1.0, v11
	v_add_f32_e32 v12, 1.0, v12
	v_add_f32_e32 v13, 1.0, v13
	v_add_f32_e32 v14, 1.0, v14
	v_add_f32_e32 v15, 1.0, v15
	v_rcp_f32_e32 v1, v1
	v_rcp_f32_e32 v2, v2
	v_rcp_f32_e32 v3, v3
	v_rcp_f32_e32 v4, v4
	v_rcp_f32_e32 v5, v5
	v_rcp_f32_e32 v6, v6
	v_rcp_f32_e32 v7, v7
	v_rcp_f32_e32 v8, v8
	v_rcp_f32_e32 v9, v9
	v_rcp_f32_e32 v10, v10
	v_rcp_f32_e32 v11, v11
	v_rcp_f32_e32 v12, v12
	v_rcp_f32_e32 v13, v13
	v_rcp_f32_e32 v14, v14
	v_rcp_f32_e32 v15, v15
	v_cvt_pk_bf16_f32 v0, v0, v1
	v_cvt_pk_bf16_f32 v1, v2, v3
	v_cvt_pk_bf16_f32 v2, v4, v5
	v_cvt_pk_bf16_f32 v3, v6, v7
	v_add_co_u32_e32 v4, vcc, 0x7000, v92
	global_store_dwordx4 v[20:21], v[0:3], off
	s_nop 0
	v_addc_co_u32_e32 v5, vcc, 0, v93, vcc
	v_cvt_pk_bf16_f32 v0, v8, v9
	v_cvt_pk_bf16_f32 v1, v10, v11
	v_cvt_pk_bf16_f32 v2, v12, v13
	v_cvt_pk_bf16_f32 v3, v14, v15
	global_store_dwordx4 v[4:5], v[0:3], off
	s_cmp_eq_u32 s62, 1
	s_cbranch_scc0 .Lgt_e2
	s_mov_b32 s62, 2
	v_mov_b32_e32 v48, v136
	v_mov_b32_e32 v49, v137
	v_mov_b32_e32 v50, v138
	v_mov_b32_e32 v51, v139
	v_mov_b32_e32 v52, v140
	v_mov_b32_e32 v53, v141
	v_mov_b32_e32 v54, v142
	v_mov_b32_e32 v55, v143
	v_mov_b32_e32 v56, v144
	v_mov_b32_e32 v57, v145
	v_mov_b32_e32 v58, v146
	v_mov_b32_e32 v59, v147
	v_mov_b32_e32 v60, v148
	v_mov_b32_e32 v61, v149
	v_mov_b32_e32 v62, v150
	v_mov_b32_e32 v63, v151
	v_mov_b32_e32 v32, v152
	v_mov_b32_e32 v33, v153
	v_mov_b32_e32 v34, v154
	v_mov_b32_e32 v35, v155
	v_mov_b32_e32 v36, v156
	v_mov_b32_e32 v37, v157
	v_mov_b32_e32 v38, v158
	v_mov_b32_e32 v39, v159
	v_mov_b32_e32 v40, v160
	v_mov_b32_e32 v41, v161
	v_mov_b32_e32 v42, v162
	v_mov_b32_e32 v43, v163
	v_mov_b32_e32 v44, v164
	v_mov_b32_e32 v45, v165
	v_mov_b32_e32 v46, v166
	v_mov_b32_e32 v47, v167
	v_mov_b32_e32 v16, v168
	v_mov_b32_e32 v17, v169
	v_mov_b32_e32 v18, v170
	v_mov_b32_e32 v19, v171
	v_mov_b32_e32 v20, v172
	v_mov_b32_e32 v21, v173
	v_mov_b32_e32 v22, v174
	v_mov_b32_e32 v23, v175
	v_mov_b32_e32 v24, v176
	v_mov_b32_e32 v25, v177
	v_mov_b32_e32 v26, v178
	v_mov_b32_e32 v27, v179
	v_mov_b32_e32 v28, v180
	v_mov_b32_e32 v29, v181
	v_mov_b32_e32 v30, v182
	v_mov_b32_e32 v31, v183
	v_mov_b32_e32 v0, v184
	v_mov_b32_e32 v1, v185
	v_mov_b32_e32 v2, v186
	v_mov_b32_e32 v3, v187
	v_mov_b32_e32 v4, v188
	v_mov_b32_e32 v5, v189
	v_mov_b32_e32 v6, v190
	v_mov_b32_e32 v7, v191
	v_mov_b32_e32 v8, v192
	v_mov_b32_e32 v9, v193
	v_mov_b32_e32 v10, v194
	v_mov_b32_e32 v11, v195
	v_mov_b32_e32 v12, v196
	v_mov_b32_e32 v13, v197
	v_mov_b32_e32 v14, v198
	v_mov_b32_e32 v15, v199
	v_mov_b32_e32 v89, v200
	v_mov_b32_e32 v91, v201
	v_mov_b32_e32 v92, v202
	v_add_u32_e32 v93, 1, v203
	s_branch .LBB0_258

.LBB0_259:
	s_barrier
	s_and_saveexec_b64 s[18:19], s[36:37]
	s_cbranch_execz .Lat_1
	v_mov_b32_e32 v226, 1
	global_atomic_add v226, v117, v226, s[0:1] sc0
.Lat_1:
	s_or_b64 exec, exec, s[18:19]
	s_xor_b64 s[16:17], s[16:17], -1
	s_mov_b32 s13, 0xaaab
	v_mul_u32_u24_sdwa v1, v0, s13 dst_sel:DWORD dst_unused:UNUSED_PAD src0_sel:WORD_0 src1_sel:DWORD
	v_lshrrev_b32_e32 v1, 21, v1
	v_mul_lo_u16_e32 v2, 48, v1
	v_sub_u16_e32 v0, v0, v2
	v_lshlrev_b16_e32 v92, 7, v0
	v_mov_b32_e32 v73, 0x358637bd
	s_and_saveexec_b64 s[18:19], s[38:39]
	s_cbranch_execz .LBB0_267
	v_lshlrev_b32_e32 v116, 2, v92
	v_lshl_add_u64 v[2:3], v[84:85], 0, v[116:117]
	global_load_dword v2, v[2:3], off
	s_waitcnt vmcnt(0)
	v_cvt_f32_u32_e32 v2, v2
	v_fmamk_f32 v73, v2, 0x36800000, v212

.LBB0_273:
	s_or_b64 exec, exec, s[16:17]
	s_and_saveexec_b64 s[18:19], s[36:37]
	s_cbranch_execz .Lat_2
	s_waitcnt vmcnt(0)
	ds_write_b32 v120, v226
.Lat_2:
	s_or_b64 exec, exec, s[18:19]
	s_waitcnt lgkmcnt(0)
	s_barrier
	ds_read_b32 v103, v120
	s_waitcnt lgkmcnt(0)
	s_mov_b32 s61, 0
	s_cmp_eq_u32 s98, 0
	s_cbranch_scc1 .Lgq_skip2
	v_readfirstlane_b32 s60, v103
	s_cmp_lt_u32 s60, 64
	s_cbranch_scc0 .Lgd_s2
	s_mov_b32 s61, 1
	s_mul_hi_u32 s13, s60, 0x2aaaaaab
	s_mul_i32 s18, s13, 6
	s_sub_i32 s18, s60, s18
	s_lshl_b32 s13, s13, 1
	s_branch .Lgd_e2

.Lgq_skip2:
	s_movk_i32 s13, 0x600
	v_cmp_gt_u32_e64 s[42:43], s13, v103
	s_movk_i32 s13, 0x5ff
	v_cmp_lt_u32_e64 s[40:41], s13, v103
	s_and_saveexec_b64 s[18:19], s[42:43]
	s_mov_b32 s13, 0xaaab
	v_mul_u32_u24_sdwa v227, v103, s13 dst_sel:DWORD dst_unused:UNUSED_PAD src0_sel:WORD_0 src1_sel:DWORD
	v_lshrrev_b32_e32 v227, 21, v227
	v_mul_lo_u16_e32 v228, 48, v227
	v_sub_u16_e32 v228, v103, v228
	v_lshlrev_b16_e32 v227, 7, v227
	v_lshlrev_b16_e32 v97, 7, v228
	v_add_u16_e32 v102, 0xe00, v227
	s_or_b64 exec, exec, s[18:19]
	s_and_saveexec_b64 s[16:17], s[42:43]
	s_cbranch_execz .LBB0_258
	v_ashrrev_i32_e32 v64, 7, v97
	v_ashrrev_i32_e32 v65, 31, v64
	v_lshlrev_b64 v[64:65], 18, v[64:65]
	v_ashrrev_i32_e32 v66, 7, v102
	v_readfirstlane_b32 s13, v94
	v_lshl_add_u64 v[64:65], v[80:81], 0, v[64:65]
	v_ashrrev_i32_e32 v67, 31, v66
	s_mov_b64 s[18:19], 0x400
	s_mov_b32 m0, s13
	v_readfirstlane_b32 s13, v79
	v_lshlrev_b64 v[66:67], 18, v[66:67]
	v_lshl_add_u64 v[104:105], v[64:65], 0, s[18:19]
	global_load_lds_dwordx4 v[64:65], off
	s_mov_b32 m0, s13
	v_readfirstlane_b32 s13, v78
	v_lshl_add_u64 v[66:67], v[82:83], 0, v[66:67]
	global_load_lds_dwordx4 v[104:105], off
	s_mov_b32 m0, s13
	v_readfirstlane_b32 s13, v77
	global_load_lds_dwordx4 v[66:67], off
	v_lshl_add_u64 v[78:79], v[66:67], 0, s[18:19]
	s_mov_b32 m0, s13
	v_readfirstlane_b32 s13, v76
	global_load_lds_dwordx4 v[78:79], off
	v_lshl_add_u64 v[78:79], v[64:65], 0, s[44:45]
	s_mov_b32 m0, s13
	v_readfirstlane_b32 s13, v75
	global_load_lds_dwordx4 v[78:79], off
	v_lshl_add_u64 v[76:77], v[64:65], 0, s[66:67]
	s_mov_b32 m0, s13
	v_readfirstlane_b32 s13, v74
	global_load_lds_dwordx4 v[76:77], off
	v_lshl_add_u64 v[76:77], v[66:67], 0, s[44:45]
	s_mov_b32 m0, s13
	v_readfirstlane_b32 s13, v72
	global_load_lds_dwordx4 v[76:77], off
	v_lshl_add_u64 v[74:75], v[66:67], 0, s[66:67]
	s_mov_b32 m0, s13
	v_readfirstlane_b32 s13, v71
	global_load_lds_dwordx4 v[74:75], off
	v_lshl_add_u64 v[72:73], v[64:65], 0, s[28:29]
	s_mov_b32 m0, s13
	s_mov_b64 s[18:19], 0x4400
	v_readfirstlane_b32 s13, v70
	global_load_lds_dwordx4 v[72:73], off
	v_lshl_add_u64 v[64:65], v[64:65], 0, s[18:19]
	s_mov_b32 m0, s13
	v_readfirstlane_b32 s13, v69
	global_load_lds_dwordx4 v[64:65], off
	v_lshl_add_u64 v[64:65], v[66:67], 0, s[28:29]
	s_mov_b32 m0, s13
	v_readfirstlane_b32 s13, v68
	global_load_lds_dwordx4 v[64:65], off
	v_lshl_add_u64 v[64:65], v[66:67], 0, s[18:19]
	s_mov_b32 m0, s13
	s_nop 0
	global_load_lds_dwordx4 v[64:65], off
	s_branch .LBB0_258
